# S5 mixer phase A: 4 U-fragment loads in flight instead of 2 (unique destination registers, counted waits)
# baseline (speedup 1.0000x reference)
.LBB5_373:
	s_and_b32 s3, s58, 63
	v_mbcnt_lo_u32_b32 v84, -1, 0
	v_mbcnt_hi_u32_b32 v84, -1, v84
	s_mul_i32 s0, s3, 0x46000
	v_add_u32_e32 v76, s81, v84
	s_add_u32 s0, s53, s0
	v_ashrrev_i32_e32 v77, 31, v76
	s_addc_u32 s1, s55, 0
	v_lshlrev_b64 v[0:1], 4, v[76:77]
	v_lshl_add_u64 v[78:79], s[0:1], 0, v[0:1]
	v_add_co_u32_e32 v4, vcc, s29, v78
	s_movk_i32 s8, 0x4000
	s_nop 0
	v_addc_co_u32_e32 v5, vcc, 0, v79, vcc
	v_add_co_u32_e32 v8, vcc, s8, v78
	s_movk_i32 s8, 0x6000
	s_nop 0
	v_addc_co_u32_e32 v9, vcc, 0, v79, vcc
	v_add_co_u32_e32 v12, vcc, s8, v78
	s_mov_b32 s8, 0x8000
	s_nop 0
	v_addc_co_u32_e32 v13, vcc, 0, v79, vcc
	v_add_co_u32_e32 v16, vcc, s8, v78
	s_mov_b32 s8, 0xa000
	s_nop 0
	v_addc_co_u32_e32 v17, vcc, 0, v79, vcc
	v_add_co_u32_e32 v20, vcc, s8, v78
	s_mov_b32 s8, 0xc000
	s_nop 0
	v_addc_co_u32_e32 v21, vcc, 0, v79, vcc
	v_add_co_u32_e32 v24, vcc, s8, v78
	s_mov_b32 s8, 0xe000
	s_nop 0
	v_addc_co_u32_e32 v25, vcc, 0, v79, vcc
	v_add_co_u32_e32 v28, vcc, s8, v78
	s_mov_b32 s8, 0x10000
	s_nop 0
	v_addc_co_u32_e32 v29, vcc, 0, v79, vcc
	v_add_co_u32_e32 v32, vcc, s8, v78
	global_load_dwordx4 v[0:3], v[78:79], off
	s_nop 0
	global_load_dwordx4 v[4:7], v[4:5], off
	v_addc_co_u32_e32 v33, vcc, 0, v79, vcc
	v_add_co_u32_e32 v36, vcc, s31, v78
	global_load_dwordx4 v[8:11], v[8:9], off
	s_nop 0
	global_load_dwordx4 v[12:15], v[12:13], off
	v_addc_co_u32_e32 v37, vcc, 0, v79, vcc
	v_add_co_u32_e32 v40, vcc, s84, v78
	global_load_dwordx4 v[16:19], v[16:17], off
	s_nop 0
	global_load_dwordx4 v[20:23], v[20:21], off
	v_addc_co_u32_e32 v41, vcc, 0, v79, vcc
	v_add_co_u32_e32 v44, vcc, s85, v78
	global_load_dwordx4 v[24:27], v[24:25], off
	s_nop 0
	global_load_dwordx4 v[28:31], v[28:29], off
	v_addc_co_u32_e32 v45, vcc, 0, v79, vcc
	v_add_co_u32_e32 v48, vcc, s86, v78
	global_load_dwordx4 v[32:35], v[32:33], off
	s_nop 0
	global_load_dwordx4 v[36:39], v[36:37], off
	v_addc_co_u32_e32 v49, vcc, 0, v79, vcc
	v_add_co_u32_e32 v52, vcc, s87, v78
	global_load_dwordx4 v[40:43], v[40:41], off
	s_nop 0
	global_load_dwordx4 v[44:47], v[44:45], off
	v_addc_co_u32_e32 v53, vcc, 0, v79, vcc
	v_add_co_u32_e32 v56, vcc, s88, v78
	global_load_dwordx4 v[48:51], v[48:49], off
	s_nop 0
	global_load_dwordx4 v[52:55], v[52:53], off
	v_addc_co_u32_e32 v57, vcc, 0, v79, vcc
	v_add_co_u32_e32 v60, vcc, s89, v78
	global_load_dwordx4 v[56:59], v[56:57], off
	s_nop 0
	v_addc_co_u32_e32 v61, vcc, 0, v79, vcc
	global_load_dwordx4 v[60:63], v[60:61], off
	v_ashrrev_i32_e32 v81, 6, v76
	s_movk_i32 s8, 0x410
	v_mul_lo_u32 v85, v81, s8
	v_lshlrev_b32_e32 v81, 4, v84
	v_and_b32_e32 v88, 0x3f0, v81
	v_add3_u32 v85, 0, v85, v88
	v_and_b32_e32 v192, 31, v84
	s_ashr_i32 s59, s58, 31
	s_lshl_b64 s[24:25], s[58:59], 18
	v_or_b32_e32 v80, s6, v192
	v_ashrrev_i32_e32 v77, 5, v84
	v_lshlrev_b32_e32 v176, 5, v80
	s_add_u32 s24, s45, s24
	v_lshlrev_b64 v[86:87], 5, v[176:177]
	s_waitcnt vmcnt(15)
	ds_write_b128 v85, v[0:3]
	s_waitcnt vmcnt(14)
	ds_write_b128 v85, v[4:7] offset:8320
	s_waitcnt vmcnt(13)
	ds_write_b128 v85, v[8:11] offset:16640
	s_waitcnt vmcnt(12)
	ds_write_b128 v85, v[12:15] offset:24960
	s_waitcnt vmcnt(11)
	ds_write_b128 v85, v[16:19] offset:33280
	s_waitcnt vmcnt(10)
	ds_write_b128 v85, v[20:23] offset:41600
	s_waitcnt vmcnt(9)
	ds_write_b128 v85, v[24:27] offset:49920
	s_waitcnt vmcnt(8)
	ds_write_b128 v85, v[28:31] offset:58240
	v_add_u32_e32 v0, 0x10400, v85
	v_lshlrev_b32_e32 v82, 3, v77
	s_addc_u32 s25, s47, s25
	s_waitcnt vmcnt(7)
	ds_write_b128 v0, v[32:35]
	v_add_u32_e32 v0, 0x12480, v85
	s_waitcnt vmcnt(6)
	ds_write_b128 v0, v[36:39]
	v_add_u32_e32 v0, 0x14500, v85
	v_ashrrev_i32_e32 v83, 31, v82
	s_waitcnt vmcnt(5)
	ds_write_b128 v0, v[40:43]
	v_add_u32_e32 v0, 0x16580, v85
	s_waitcnt vmcnt(4)
	ds_write_b128 v0, v[44:47]
	v_add_u32_e32 v0, 0x18600, v85
	s_waitcnt vmcnt(3)
	ds_write_b128 v0, v[48:51]
	v_add_u32_e32 v0, 0x1a680, v85
	s_waitcnt vmcnt(2)
	ds_write_b128 v0, v[52:55]
	v_add_u32_e32 v0, 0x1c700, v85
	s_waitcnt vmcnt(1)
	ds_write_b128 v0, v[56:59]
	v_add_u32_e32 v0, 0x1e780, v85
	s_waitcnt vmcnt(0)
	ds_write_b128 v0, v[60:63]
	v_lshl_add_u64 v[0:1], s[24:25], 0, v[86:87]
	v_lshl_add_u64 v[178:179], v[82:83], 1, v[0:1]
	s_waitcnt lgkmcnt(0)
	s_barrier
	global_load_dwordx4 v[116:119], v[178:179], off
	global_load_dwordx4 v[120:123], v[178:179], off offset:32
	global_load_dwordx4 v[124:127], v[178:179], off offset:64
	global_load_dwordx4 v[128:131], v[178:179], off offset:96
	v_mul_u32_u24_e32 v0, 0x410, v192
	v_lshlrev_b32_e32 v87, 4, v77
	v_add3_u32 v85, 0, v0, v87
	ds_read_b128 v[0:3], v85
	ds_read_b128 v[92:95], v85 offset:32
	v_add_u32_e32 v4, 0x18600, v85
	v_add_u32_e32 v86, 0x10420, v85
	s_waitcnt vmcnt(3) lgkmcnt(1)
	v_mfma_f32_32x32x16_bf16 v[32:47], v[116:119], v[0:3], 0
	ds_read_b128 v[0:3], v85 offset:33280
	ds_read_b128 v[96:99], v85 offset:33312
	ds_read_b128 v[20:23], v4
	s_waitcnt lgkmcnt(2)
	v_mfma_f32_32x32x16_bf16 v[48:63], v[116:119], v[0:3], 0
	v_add_u32_e32 v0, 0x10400, v85
	ds_read_b128 v[0:3], v0
	s_waitcnt lgkmcnt(0)
	v_mfma_f32_32x32x16_bf16 v[0:15], v[116:119], v[0:3], 0
	s_waitcnt vmcnt(2)
	v_mfma_f32_32x32x16_bf16 v[32:47], v[120:123], v[92:95], v[32:47]
	ds_read_b128 v[92:95], v86
	v_add_u32_e32 v86, 0x18620, v85
	s_waitcnt lgkmcnt(0)
	v_mfma_f32_32x32x16_bf16 v[0:15], v[120:123], v[92:95], v[0:15]
	global_load_dwordx4 v[132:135], v[178:179], off offset:128
	v_mfma_f32_32x32x16_bf16 v[16:31], v[116:119], v[20:23], 0
	v_mfma_f32_32x32x16_bf16 v[48:63], v[120:123], v[96:99], v[48:63]
	ds_read_b128 v[96:99], v86
	v_add_u32_e32 v86, 0x10440, v85
	s_waitcnt lgkmcnt(0)
	v_mfma_f32_32x32x16_bf16 v[16:31], v[120:123], v[96:99], v[16:31]
	global_load_dwordx4 v[136:139], v[178:179], off offset:160
	ds_read_b128 v[96:99], v85 offset:64
	ds_read_b128 v[100:103], v85 offset:96
	s_waitcnt vmcnt(3) lgkmcnt(1)
	v_mfma_f32_32x32x16_bf16 v[32:47], v[124:127], v[96:99], v[32:47]
	ds_read_b128 v[96:99], v85 offset:33344
	ds_read_b128 v[104:107], v85 offset:33376
	s_waitcnt lgkmcnt(1)
	v_mfma_f32_32x32x16_bf16 v[48:63], v[124:127], v[96:99], v[48:63]
	ds_read_b128 v[96:99], v86
	v_add_u32_e32 v86, 0x18640, v85
	ds_read_b128 v[108:111], v86
	v_add_u32_e32 v86, 0x10460, v85
	s_waitcnt lgkmcnt(1)
	v_mfma_f32_32x32x16_bf16 v[0:15], v[124:127], v[96:99], v[0:15]
	s_waitcnt lgkmcnt(0)
	v_mfma_f32_32x32x16_bf16 v[16:31], v[124:127], v[108:111], v[16:31]
	ds_read_b128 v[92:95], v86
	v_add_u32_e32 v86, 0x18660, v85
	ds_read_b128 v[96:99], v86
	v_add_u32_e32 v86, 0x10480, v85
	s_waitcnt vmcnt(2) lgkmcnt(1)
	v_mfma_f32_32x32x16_bf16 v[0:15], v[128:131], v[92:95], v[0:15]
	global_load_dwordx4 v[140:143], v[178:179], off offset:192
	v_mfma_f32_32x32x16_bf16 v[32:47], v[128:131], v[100:103], v[32:47]
	v_mfma_f32_32x32x16_bf16 v[48:63], v[128:131], v[104:107], v[48:63]
	s_waitcnt lgkmcnt(0)
	v_mfma_f32_32x32x16_bf16 v[16:31], v[128:131], v[96:99], v[16:31]
	global_load_dwordx4 v[144:147], v[178:179], off offset:224
	ds_read_b128 v[96:99], v85 offset:128
	ds_read_b128 v[100:103], v85 offset:160
	s_waitcnt vmcnt(3) lgkmcnt(1)
	v_mfma_f32_32x32x16_bf16 v[32:47], v[132:135], v[96:99], v[32:47]
	ds_read_b128 v[96:99], v85 offset:33408
	ds_read_b128 v[104:107], v85 offset:33440
	s_waitcnt lgkmcnt(1)
	v_mfma_f32_32x32x16_bf16 v[48:63], v[132:135], v[96:99], v[48:63]
	ds_read_b128 v[96:99], v86
	v_add_u32_e32 v86, 0x18680, v85
	ds_read_b128 v[108:111], v86
	v_add_u32_e32 v86, 0x104a0, v85
	s_waitcnt lgkmcnt(1)
	v_mfma_f32_32x32x16_bf16 v[0:15], v[132:135], v[96:99], v[0:15]
	s_waitcnt lgkmcnt(0)
	v_mfma_f32_32x32x16_bf16 v[16:31], v[132:135], v[108:111], v[16:31]
	ds_read_b128 v[92:95], v86
	v_add_u32_e32 v86, 0x186a0, v85
	ds_read_b128 v[96:99], v86
	v_add_u32_e32 v86, 0x104c0, v85
	s_waitcnt vmcnt(2) lgkmcnt(1)
	v_mfma_f32_32x32x16_bf16 v[0:15], v[136:139], v[92:95], v[0:15]
	global_load_dwordx4 v[148:151], v[178:179], off offset:256
	v_mfma_f32_32x32x16_bf16 v[32:47], v[136:139], v[100:103], v[32:47]
	v_mfma_f32_32x32x16_bf16 v[48:63], v[136:139], v[104:107], v[48:63]
	s_waitcnt lgkmcnt(0)
	v_mfma_f32_32x32x16_bf16 v[16:31], v[136:139], v[96:99], v[16:31]
	global_load_dwordx4 v[152:155], v[178:179], off offset:288
	ds_read_b128 v[96:99], v85 offset:192
	ds_read_b128 v[100:103], v85 offset:224
	s_waitcnt vmcnt(3) lgkmcnt(1)
	v_mfma_f32_32x32x16_bf16 v[32:47], v[140:143], v[96:99], v[32:47]
	ds_read_b128 v[96:99], v85 offset:33472
	ds_read_b128 v[104:107], v85 offset:33504
	s_waitcnt lgkmcnt(1)
	v_mfma_f32_32x32x16_bf16 v[48:63], v[140:143], v[96:99], v[48:63]
	ds_read_b128 v[96:99], v86
	v_add_u32_e32 v86, 0x186c0, v85
	ds_read_b128 v[108:111], v86
	v_add_u32_e32 v86, 0x104e0, v85
	s_waitcnt lgkmcnt(1)
	v_mfma_f32_32x32x16_bf16 v[0:15], v[140:143], v[96:99], v[0:15]
	s_waitcnt lgkmcnt(0)
	v_mfma_f32_32x32x16_bf16 v[16:31], v[140:143], v[108:111], v[16:31]
	ds_read_b128 v[92:95], v86
	v_add_u32_e32 v86, 0x186e0, v85
	ds_read_b128 v[96:99], v86
	v_add_u32_e32 v86, 0x10500, v85
	s_waitcnt vmcnt(2) lgkmcnt(1)
	v_mfma_f32_32x32x16_bf16 v[0:15], v[144:147], v[92:95], v[0:15]
	global_load_dwordx4 v[156:159], v[178:179], off offset:320
	v_mfma_f32_32x32x16_bf16 v[32:47], v[144:147], v[100:103], v[32:47]
	v_mfma_f32_32x32x16_bf16 v[48:63], v[144:147], v[104:107], v[48:63]
	s_waitcnt lgkmcnt(0)
	v_mfma_f32_32x32x16_bf16 v[16:31], v[144:147], v[96:99], v[16:31]
	global_load_dwordx4 v[160:163], v[178:179], off offset:352
	ds_read_b128 v[96:99], v85 offset:256
	ds_read_b128 v[100:103], v85 offset:288
	s_waitcnt vmcnt(3) lgkmcnt(1)
	v_mfma_f32_32x32x16_bf16 v[32:47], v[148:151], v[96:99], v[32:47]
	ds_read_b128 v[96:99], v85 offset:33536
	ds_read_b128 v[104:107], v85 offset:33568
	s_waitcnt lgkmcnt(1)
	v_mfma_f32_32x32x16_bf16 v[48:63], v[148:151], v[96:99], v[48:63]
	ds_read_b128 v[96:99], v86
	v_add_u32_e32 v86, 0x18700, v85
	ds_read_b128 v[108:111], v86
	v_add_u32_e32 v86, 0x10520, v85
	s_waitcnt lgkmcnt(1)
	v_mfma_f32_32x32x16_bf16 v[0:15], v[148:151], v[96:99], v[0:15]
	s_waitcnt lgkmcnt(0)
	v_mfma_f32_32x32x16_bf16 v[16:31], v[148:151], v[108:111], v[16:31]
	ds_read_b128 v[92:95], v86
	v_add_u32_e32 v86, 0x18720, v85
	ds_read_b128 v[96:99], v86
	v_add_u32_e32 v86, 0x10540, v85
	s_waitcnt vmcnt(2) lgkmcnt(1)
	v_mfma_f32_32x32x16_bf16 v[0:15], v[152:155], v[92:95], v[0:15]
	global_load_dwordx4 v[164:167], v[178:179], off offset:384
	v_mfma_f32_32x32x16_bf16 v[32:47], v[152:155], v[100:103], v[32:47]
	v_mfma_f32_32x32x16_bf16 v[48:63], v[152:155], v[104:107], v[48:63]
	s_waitcnt lgkmcnt(0)
	v_mfma_f32_32x32x16_bf16 v[16:31], v[152:155], v[96:99], v[16:31]
	global_load_dwordx4 v[168:171], v[178:179], off offset:416
	ds_read_b128 v[96:99], v85 offset:320
	ds_read_b128 v[100:103], v85 offset:352
	s_waitcnt vmcnt(3) lgkmcnt(1)
	v_mfma_f32_32x32x16_bf16 v[32:47], v[156:159], v[96:99], v[32:47]
	ds_read_b128 v[96:99], v85 offset:33600
	ds_read_b128 v[104:107], v85 offset:33632
	s_waitcnt lgkmcnt(1)
	v_mfma_f32_32x32x16_bf16 v[48:63], v[156:159], v[96:99], v[48:63]
	ds_read_b128 v[96:99], v86
	v_add_u32_e32 v86, 0x18740, v85
	ds_read_b128 v[108:111], v86
	v_add_u32_e32 v86, 0x10560, v85
	s_waitcnt lgkmcnt(1)
	v_mfma_f32_32x32x16_bf16 v[0:15], v[156:159], v[96:99], v[0:15]
	s_waitcnt lgkmcnt(0)
	v_mfma_f32_32x32x16_bf16 v[16:31], v[156:159], v[108:111], v[16:31]
	ds_read_b128 v[92:95], v86
	v_add_u32_e32 v86, 0x18760, v85
	ds_read_b128 v[96:99], v86
	v_add_u32_e32 v86, 0x10580, v85
	s_waitcnt vmcnt(2) lgkmcnt(1)
	v_mfma_f32_32x32x16_bf16 v[0:15], v[160:163], v[92:95], v[0:15]
	global_load_dwordx4 v[172:175], v[178:179], off offset:448
	v_mfma_f32_32x32x16_bf16 v[32:47], v[160:163], v[100:103], v[32:47]
	v_mfma_f32_32x32x16_bf16 v[48:63], v[160:163], v[104:107], v[48:63]
	s_waitcnt lgkmcnt(0)
	v_mfma_f32_32x32x16_bf16 v[16:31], v[160:163], v[96:99], v[16:31]
	global_load_dwordx4 v[196:199], v[178:179], off offset:480
	ds_read_b128 v[96:99], v85 offset:384
	ds_read_b128 v[100:103], v85 offset:416
	s_waitcnt vmcnt(3) lgkmcnt(1)
	v_mfma_f32_32x32x16_bf16 v[32:47], v[164:167], v[96:99], v[32:47]
	ds_read_b128 v[96:99], v85 offset:33664
	ds_read_b128 v[104:107], v85 offset:33696
	s_waitcnt lgkmcnt(1)
	v_mfma_f32_32x32x16_bf16 v[48:63], v[164:167], v[96:99], v[48:63]
	ds_read_b128 v[96:99], v86
	v_add_u32_e32 v86, 0x18780, v85
	ds_read_b128 v[108:111], v86
	v_add_u32_e32 v86, 0x105a0, v85
	s_waitcnt lgkmcnt(1)
	v_mfma_f32_32x32x16_bf16 v[0:15], v[164:167], v[96:99], v[0:15]
	s_waitcnt lgkmcnt(0)
	v_mfma_f32_32x32x16_bf16 v[16:31], v[164:167], v[108:111], v[16:31]
	ds_read_b128 v[92:95], v86
	v_add_u32_e32 v86, 0x187a0, v85
	ds_read_b128 v[96:99], v86
	v_add_u32_e32 v86, 0x105c0, v85
	s_waitcnt vmcnt(2) lgkmcnt(1)
	v_mfma_f32_32x32x16_bf16 v[0:15], v[168:171], v[92:95], v[0:15]
	global_load_dwordx4 v[200:203], v[178:179], off offset:512
	v_mfma_f32_32x32x16_bf16 v[32:47], v[168:171], v[100:103], v[32:47]
	v_mfma_f32_32x32x16_bf16 v[48:63], v[168:171], v[104:107], v[48:63]
	s_waitcnt lgkmcnt(0)
	v_mfma_f32_32x32x16_bf16 v[16:31], v[168:171], v[96:99], v[16:31]
	global_load_dwordx4 v[204:207], v[178:179], off offset:544
	ds_read_b128 v[96:99], v85 offset:448
	ds_read_b128 v[100:103], v85 offset:480
	s_waitcnt vmcnt(3) lgkmcnt(1)
	v_mfma_f32_32x32x16_bf16 v[32:47], v[172:175], v[96:99], v[32:47]
	ds_read_b128 v[96:99], v85 offset:33728
	ds_read_b128 v[104:107], v85 offset:33760
	s_waitcnt lgkmcnt(1)
	v_mfma_f32_32x32x16_bf16 v[48:63], v[172:175], v[96:99], v[48:63]
	ds_read_b128 v[96:99], v86
	v_add_u32_e32 v86, 0x187c0, v85
	ds_read_b128 v[108:111], v86
	v_add_u32_e32 v86, 0x105e0, v85
	s_waitcnt lgkmcnt(1)
	v_mfma_f32_32x32x16_bf16 v[0:15], v[172:175], v[96:99], v[0:15]
	s_waitcnt lgkmcnt(0)
	v_mfma_f32_32x32x16_bf16 v[16:31], v[172:175], v[108:111], v[16:31]
	ds_read_b128 v[92:95], v86
	v_add_u32_e32 v86, 0x187e0, v85
	ds_read_b128 v[96:99], v86
	v_add_u32_e32 v86, 0x10600, v85
	s_waitcnt vmcnt(2) lgkmcnt(1)
	v_mfma_f32_32x32x16_bf16 v[0:15], v[196:199], v[92:95], v[0:15]
	global_load_dwordx4 v[208:211], v[178:179], off offset:576
	v_mfma_f32_32x32x16_bf16 v[32:47], v[196:199], v[100:103], v[32:47]
	v_mfma_f32_32x32x16_bf16 v[48:63], v[196:199], v[104:107], v[48:63]
	s_waitcnt lgkmcnt(0)
	v_mfma_f32_32x32x16_bf16 v[16:31], v[196:199], v[96:99], v[16:31]
	global_load_dwordx4 v[212:215], v[178:179], off offset:608
	ds_read_b128 v[96:99], v85 offset:512
	ds_read_b128 v[100:103], v85 offset:544
	s_waitcnt vmcnt(3) lgkmcnt(1)
	v_mfma_f32_32x32x16_bf16 v[32:47], v[200:203], v[96:99], v[32:47]
	ds_read_b128 v[96:99], v85 offset:33792
	ds_read_b128 v[104:107], v85 offset:33824
	s_waitcnt lgkmcnt(1)
	v_mfma_f32_32x32x16_bf16 v[48:63], v[200:203], v[96:99], v[48:63]
	ds_read_b128 v[96:99], v86
	v_add_u32_e32 v86, 0x18800, v85
	ds_read_b128 v[108:111], v86
	v_add_u32_e32 v86, 0x10620, v85
	s_waitcnt lgkmcnt(1)
	v_mfma_f32_32x32x16_bf16 v[0:15], v[200:203], v[96:99], v[0:15]
	s_waitcnt lgkmcnt(0)
	v_mfma_f32_32x32x16_bf16 v[16:31], v[200:203], v[108:111], v[16:31]
	ds_read_b128 v[92:95], v86
	v_add_u32_e32 v86, 0x18820, v85
	ds_read_b128 v[96:99], v86
	v_add_u32_e32 v86, 0x10640, v85
	s_waitcnt vmcnt(2) lgkmcnt(1)
	v_mfma_f32_32x32x16_bf16 v[0:15], v[204:207], v[92:95], v[0:15]
	global_load_dwordx4 v[216:219], v[178:179], off offset:640
	v_mfma_f32_32x32x16_bf16 v[32:47], v[204:207], v[100:103], v[32:47]
	v_mfma_f32_32x32x16_bf16 v[48:63], v[204:207], v[104:107], v[48:63]
	s_waitcnt lgkmcnt(0)
	v_mfma_f32_32x32x16_bf16 v[16:31], v[204:207], v[96:99], v[16:31]
	global_load_dwordx4 v[220:223], v[178:179], off offset:672
	ds_read_b128 v[96:99], v85 offset:576
	ds_read_b128 v[100:103], v85 offset:608
	s_waitcnt vmcnt(3) lgkmcnt(1)
	v_mfma_f32_32x32x16_bf16 v[32:47], v[208:211], v[96:99], v[32:47]
	ds_read_b128 v[96:99], v85 offset:33856
	ds_read_b128 v[104:107], v85 offset:33888
	s_waitcnt lgkmcnt(1)
	v_mfma_f32_32x32x16_bf16 v[48:63], v[208:211], v[96:99], v[48:63]
	ds_read_b128 v[96:99], v86
	v_add_u32_e32 v86, 0x18840, v85
	ds_read_b128 v[108:111], v86
	v_add_u32_e32 v86, 0x10660, v85
	s_waitcnt lgkmcnt(1)
	v_mfma_f32_32x32x16_bf16 v[0:15], v[208:211], v[96:99], v[0:15]
	s_waitcnt lgkmcnt(0)
	v_mfma_f32_32x32x16_bf16 v[16:31], v[208:211], v[108:111], v[16:31]
	ds_read_b128 v[92:95], v86
	v_add_u32_e32 v86, 0x18860, v85
	ds_read_b128 v[96:99], v86
	v_add_u32_e32 v86, 0x10680, v85
	s_waitcnt vmcnt(2) lgkmcnt(1)
	v_mfma_f32_32x32x16_bf16 v[0:15], v[212:215], v[92:95], v[0:15]
	global_load_dwordx4 v[224:227], v[178:179], off offset:704
	v_mfma_f32_32x32x16_bf16 v[32:47], v[212:215], v[100:103], v[32:47]
	v_mfma_f32_32x32x16_bf16 v[48:63], v[212:215], v[104:107], v[48:63]
	s_waitcnt lgkmcnt(0)
	v_mfma_f32_32x32x16_bf16 v[16:31], v[212:215], v[96:99], v[16:31]
	global_load_dwordx4 v[228:231], v[178:179], off offset:736
	ds_read_b128 v[96:99], v85 offset:640
	ds_read_b128 v[100:103], v85 offset:672
	s_waitcnt vmcnt(3) lgkmcnt(1)
	v_mfma_f32_32x32x16_bf16 v[32:47], v[216:219], v[96:99], v[32:47]
	ds_read_b128 v[96:99], v85 offset:33920
	ds_read_b128 v[104:107], v85 offset:33952
	s_waitcnt lgkmcnt(1)
	v_mfma_f32_32x32x16_bf16 v[48:63], v[216:219], v[96:99], v[48:63]
	ds_read_b128 v[96:99], v86
	v_add_u32_e32 v86, 0x18880, v85
	ds_read_b128 v[108:111], v86
	v_add_u32_e32 v86, 0x106a0, v85
	s_waitcnt lgkmcnt(1)
	v_mfma_f32_32x32x16_bf16 v[0:15], v[216:219], v[96:99], v[0:15]
	s_waitcnt lgkmcnt(0)
	v_mfma_f32_32x32x16_bf16 v[16:31], v[216:219], v[108:111], v[16:31]
	ds_read_b128 v[92:95], v86
	v_add_u32_e32 v86, 0x188a0, v85
	ds_read_b128 v[96:99], v86
	v_add_u32_e32 v86, 0x106c0, v85
	s_waitcnt vmcnt(2) lgkmcnt(1)
	v_mfma_f32_32x32x16_bf16 v[0:15], v[220:223], v[92:95], v[0:15]
	global_load_dwordx4 v[232:235], v[178:179], off offset:768
	v_mfma_f32_32x32x16_bf16 v[32:47], v[220:223], v[100:103], v[32:47]
	v_mfma_f32_32x32x16_bf16 v[48:63], v[220:223], v[104:107], v[48:63]
	s_waitcnt lgkmcnt(0)
	v_mfma_f32_32x32x16_bf16 v[16:31], v[220:223], v[96:99], v[16:31]
	global_load_dwordx4 v[236:239], v[178:179], off offset:800
	ds_read_b128 v[96:99], v85 offset:704
	ds_read_b128 v[100:103], v85 offset:736
	s_waitcnt vmcnt(3) lgkmcnt(1)
	v_mfma_f32_32x32x16_bf16 v[32:47], v[224:227], v[96:99], v[32:47]
	ds_read_b128 v[96:99], v85 offset:33984
	ds_read_b128 v[104:107], v85 offset:34016
	s_waitcnt lgkmcnt(1)
	v_mfma_f32_32x32x16_bf16 v[48:63], v[224:227], v[96:99], v[48:63]
	ds_read_b128 v[96:99], v86
	v_add_u32_e32 v86, 0x188c0, v85
	ds_read_b128 v[108:111], v86
	v_add_u32_e32 v86, 0x106e0, v85
	s_waitcnt lgkmcnt(1)
	v_mfma_f32_32x32x16_bf16 v[0:15], v[224:227], v[96:99], v[0:15]
	s_waitcnt lgkmcnt(0)
	v_mfma_f32_32x32x16_bf16 v[16:31], v[224:227], v[108:111], v[16:31]
	ds_read_b128 v[92:95], v86
	v_add_u32_e32 v86, 0x188e0, v85
	ds_read_b128 v[96:99], v86
	v_add_u32_e32 v86, 0x10700, v85
	s_waitcnt vmcnt(2) lgkmcnt(1)
	v_mfma_f32_32x32x16_bf16 v[0:15], v[228:231], v[92:95], v[0:15]
	global_load_dwordx4 v[240:243], v[178:179], off offset:832
	v_mfma_f32_32x32x16_bf16 v[32:47], v[228:231], v[100:103], v[32:47]
	v_mfma_f32_32x32x16_bf16 v[48:63], v[228:231], v[104:107], v[48:63]
	s_waitcnt lgkmcnt(0)
	v_mfma_f32_32x32x16_bf16 v[16:31], v[228:231], v[96:99], v[16:31]
	global_load_dwordx4 v[244:247], v[178:179], off offset:864
	ds_read_b128 v[96:99], v85 offset:768
	ds_read_b128 v[100:103], v85 offset:800
	s_waitcnt vmcnt(3) lgkmcnt(1)
	v_mfma_f32_32x32x16_bf16 v[32:47], v[232:235], v[96:99], v[32:47]
	ds_read_b128 v[96:99], v85 offset:34048
	ds_read_b128 v[104:107], v85 offset:34080
	s_waitcnt lgkmcnt(1)
	v_mfma_f32_32x32x16_bf16 v[48:63], v[232:235], v[96:99], v[48:63]
	ds_read_b128 v[96:99], v86
	v_add_u32_e32 v86, 0x18900, v85
	ds_read_b128 v[108:111], v86
	v_add_u32_e32 v86, 0x10720, v85
	s_waitcnt lgkmcnt(1)
	v_mfma_f32_32x32x16_bf16 v[0:15], v[232:235], v[96:99], v[0:15]
	s_waitcnt lgkmcnt(0)
	v_mfma_f32_32x32x16_bf16 v[16:31], v[232:235], v[108:111], v[16:31]
	ds_read_b128 v[92:95], v86
	v_add_u32_e32 v86, 0x18920, v85
	ds_read_b128 v[96:99], v86
	v_add_u32_e32 v86, 0x10740, v85
	s_waitcnt vmcnt(2) lgkmcnt(1)
	v_mfma_f32_32x32x16_bf16 v[0:15], v[236:239], v[92:95], v[0:15]
	global_load_dwordx4 v[180:183], v[178:179], off offset:896
	v_mfma_f32_32x32x16_bf16 v[32:47], v[236:239], v[100:103], v[32:47]
	v_mfma_f32_32x32x16_bf16 v[48:63], v[236:239], v[104:107], v[48:63]
	s_waitcnt lgkmcnt(0)
	v_mfma_f32_32x32x16_bf16 v[16:31], v[236:239], v[96:99], v[16:31]
	global_load_dwordx4 v[184:187], v[178:179], off offset:928
	ds_read_b128 v[96:99], v85 offset:832
	ds_read_b128 v[100:103], v85 offset:864
	s_waitcnt vmcnt(3) lgkmcnt(1)
	v_mfma_f32_32x32x16_bf16 v[32:47], v[240:243], v[96:99], v[32:47]
	ds_read_b128 v[96:99], v85 offset:34112
	ds_read_b128 v[104:107], v85 offset:34144
	s_waitcnt lgkmcnt(1)
	v_mfma_f32_32x32x16_bf16 v[48:63], v[240:243], v[96:99], v[48:63]
	ds_read_b128 v[96:99], v86
	v_add_u32_e32 v86, 0x18940, v85
	ds_read_b128 v[108:111], v86
	v_add_u32_e32 v86, 0x10760, v85
	s_waitcnt lgkmcnt(1)
	v_mfma_f32_32x32x16_bf16 v[0:15], v[240:243], v[96:99], v[0:15]
	s_waitcnt lgkmcnt(0)
	v_mfma_f32_32x32x16_bf16 v[16:31], v[240:243], v[108:111], v[16:31]
	ds_read_b128 v[92:95], v86
	v_add_u32_e32 v86, 0x18960, v85
	ds_read_b128 v[96:99], v86
	v_add_u32_e32 v86, 0x10780, v85
	s_waitcnt vmcnt(2) lgkmcnt(1)
	v_mfma_f32_32x32x16_bf16 v[0:15], v[244:247], v[92:95], v[0:15]
	global_load_dwordx4 v[188:191], v[178:179], off offset:960
	v_mfma_f32_32x32x16_bf16 v[32:47], v[244:247], v[100:103], v[32:47]
	v_mfma_f32_32x32x16_bf16 v[48:63], v[244:247], v[104:107], v[48:63]
	s_waitcnt lgkmcnt(0)
	v_mfma_f32_32x32x16_bf16 v[16:31], v[244:247], v[96:99], v[16:31]
	global_load_dwordx4 v[252:255], v[178:179], off offset:992
	ds_read_b128 v[96:99], v85 offset:896
	ds_read_b128 v[100:103], v85 offset:928
	s_waitcnt vmcnt(3) lgkmcnt(1)
	v_mfma_f32_32x32x16_bf16 v[32:47], v[180:183], v[96:99], v[32:47]
	ds_read_b128 v[96:99], v85 offset:34176
	ds_read_b128 v[104:107], v85 offset:34208
	s_waitcnt lgkmcnt(1)
	v_mfma_f32_32x32x16_bf16 v[48:63], v[180:183], v[96:99], v[48:63]
	ds_read_b128 v[96:99], v86
	v_add_u32_e32 v86, 0x18980, v85
	ds_read_b128 v[108:111], v86
	v_add_u32_e32 v86, 0x107a0, v85
	s_waitcnt lgkmcnt(1)
	v_mfma_f32_32x32x16_bf16 v[0:15], v[180:183], v[96:99], v[0:15]
	s_waitcnt lgkmcnt(0)
	v_mfma_f32_32x32x16_bf16 v[16:31], v[180:183], v[108:111], v[16:31]
	ds_read_b128 v[92:95], v86
	v_add_u32_e32 v86, 0x189a0, v85
	ds_read_b128 v[96:99], v86
	v_add_u32_e32 v86, 0x107c0, v85
	v_add_u32_e32 v108, 0x189c0, v85
	s_waitcnt vmcnt(2) lgkmcnt(1)
	v_mfma_f32_32x32x16_bf16 v[0:15], v[184:187], v[92:95], v[0:15]
	v_mfma_f32_32x32x16_bf16 v[32:47], v[184:187], v[100:103], v[32:47]
	v_mfma_f32_32x32x16_bf16 v[48:63], v[184:187], v[104:107], v[48:63]
	s_waitcnt lgkmcnt(0)
	v_mfma_f32_32x32x16_bf16 v[16:31], v[184:187], v[96:99], v[16:31]
	ds_read_b128 v[96:99], v85 offset:960
	ds_read_b128 v[100:103], v85 offset:992
	s_waitcnt vmcnt(1) lgkmcnt(1)
	v_mfma_f32_32x32x16_bf16 v[32:47], v[188:191], v[96:99], v[32:47]
	ds_read_b128 v[96:99], v85 offset:34240
	ds_read_b128 v[104:107], v85 offset:34272
	s_waitcnt lgkmcnt(1)
	v_mfma_f32_32x32x16_bf16 v[48:63], v[188:191], v[96:99], v[48:63]
	s_waitcnt vmcnt(0)
	v_mfma_f32_32x32x16_bf16 v[32:47], v[252:255], v[100:103], v[32:47]
	ds_read_b128 v[96:99], v86
	ds_read_b128 v[100:103], v108
	v_add_u32_e32 v86, 0x107e0, v85
	v_add_u32_e32 v85, 0x189e0, v85
	ds_read_b128 v[108:111], v86
	ds_read_b128 v[112:115], v85
	v_lshlrev_b32_e32 v86, 2, v77
	v_lshlrev_b32_e32 v85, 2, v192
	s_waitcnt lgkmcnt(0)
	v_mfma_f32_32x32x16_bf16 v[0:15], v[188:191], v[96:99], v[0:15]
	s_barrier
	v_mfma_f32_32x32x16_bf16 v[16:31], v[188:191], v[100:103], v[16:31]
	v_mfma_f32_32x32x16_bf16 v[48:63], v[252:255], v[104:107], v[48:63]
	v_add_lshl_u32 v104, v86, s6, 9
	v_add3_u32 v85, 0, v85, v104
	s_nop 9
	ds_write2_b32 v85, v32, v48 offset1:32
	ds_write2_b32 v85, v33, v49 offset0:128 offset1:160
	v_mfma_f32_32x32x16_bf16 v[0:15], v[252:255], v[108:111], v[0:15]
	v_add_u32_e32 v32, 0x400, v85
	ds_write2_b32 v32, v34, v50 offset1:32
	ds_write2_b32 v32, v35, v51 offset0:128 offset1:160
	v_add_u32_e32 v33, 0x1000, v85
	v_add_u32_e32 v34, 0x1400, v85
	ds_write2_b32 v33, v36, v52 offset1:32
	ds_write2_b32 v33, v37, v53 offset0:128 offset1:160
	ds_write2_b32 v34, v38, v54 offset1:32
	ds_write2_b32 v34, v39, v55 offset0:128 offset1:160
	v_add_u32_e32 v35, 0x2000, v85
	v_mfma_f32_32x32x16_bf16 v[16:31], v[252:255], v[112:115], v[16:31]
	v_add_u32_e32 v36, 0x2400, v85
	v_add_u32_e32 v37, 0x3000, v85
	v_add_u32_e32 v38, 0x3400, v85
	ds_write2_b32 v35, v40, v56 offset1:32
	ds_write2_b32 v35, v41, v57 offset0:128 offset1:160
	ds_write2_b32 v36, v42, v58 offset1:32
	ds_write2_b32 v36, v43, v59 offset0:128 offset1:160
	ds_write2_b32 v37, v44, v60 offset1:32
	ds_write2_b32 v37, v45, v61 offset0:128 offset1:160
	ds_write2_b32 v38, v46, v62 offset1:32
	ds_write2_b32 v38, v47, v63 offset0:128 offset1:160
	s_nop 0
	ds_write2_b32 v85, v0, v16 offset0:64 offset1:96
	ds_write2_b32 v85, v1, v17 offset0:192 offset1:224
	ds_write2_b32 v32, v2, v18 offset0:64 offset1:96
	ds_write2_b32 v32, v3, v19 offset0:192 offset1:224
	ds_write2_b32 v33, v4, v20 offset0:64 offset1:96
	ds_write2_b32 v33, v5, v21 offset0:192 offset1:224
	ds_write2_b32 v34, v6, v22 offset0:64 offset1:96
	ds_write2_b32 v34, v7, v23 offset0:192 offset1:224
	ds_write2_b32 v35, v8, v24 offset0:64 offset1:96
	ds_write2_b32 v35, v9, v25 offset0:192 offset1:224
	ds_write2_b32 v36, v10, v26 offset0:64 offset1:96
	ds_write2_b32 v36, v11, v27 offset0:192 offset1:224
	ds_write2_b32 v37, v12, v28 offset0:64 offset1:96
	ds_write2_b32 v37, v13, v29 offset0:192 offset1:224
	ds_write2_b32 v38, v14, v30 offset0:64 offset1:96
	ds_write2_b32 v38, v15, v31 offset0:192 offset1:224
	v_ashrrev_i32_e32 v85, 31, v84
	v_lshl_add_u64 v[0:1], v[84:85], 2, s[0:1]
	v_lshl_add_u64 v[2:3], v[0:1], 0, s[20:21]
	v_add_co_u32_e32 v0, vcc, s92, v0
	s_waitcnt lgkmcnt(0)
	s_nop 0
	v_addc_co_u32_e32 v1, vcc, 0, v1, vcc
	s_barrier
	global_load_dword v0, v[0:1], off offset:512
	s_nop 0
	global_load_dword v2, v[2:3], off offset:256
	v_lshl_add_u32 v10, v84, 2, s82
	ds_read2st64_b32 v[4:5], v10 offset1:1
	ds_read2st64_b32 v[6:7], v10 offset0:2 offset1:3
	ds_read2st64_b32 v[8:9], v10 offset0:4 offset1:5
	ds_read2st64_b32 v[12:13], v10 offset0:6 offset1:7
	ds_read2st64_b32 v[14:15], v10 offset0:8 offset1:9
	ds_read2st64_b32 v[16:17], v10 offset0:10 offset1:11
	ds_read2st64_b32 v[18:19], v10 offset0:12 offset1:13
	ds_read2st64_b32 v[20:21], v10 offset0:14 offset1:15
	s_andn2_b64 vcc, exec, s[10:11]
	s_waitcnt vmcnt(1)
	v_mul_f32_e32 v1, 0, v0
	s_waitcnt vmcnt(0)
	v_mul_f32_e32 v23, 0, v2
	v_sub_f32_e32 v22, v1, v23
	v_fmac_f32_e32 v23, 0, v0
	s_waitcnt lgkmcnt(7)
	v_pk_add_f32 v[4:5], v[4:5], v[22:23]
	s_nop 0
	v_pk_mul_f32 v[22:23], v[2:3], v[4:5] op_sel_hi:[0,1]
	v_pk_fma_f32 v[24:25], v[0:1], v[4:5], v[22:23] op_sel:[0,0,1] op_sel_hi:[1,1,0] neg_lo:[0,0,1] neg_hi:[0,0,1]
	v_pk_fma_f32 v[4:5], v[0:1], v[4:5], v[22:23] op_sel:[0,0,1] op_sel_hi:[0,1,0]
	v_mov_b32_e32 v25, v5
	s_waitcnt lgkmcnt(6)
	v_pk_add_f32 v[4:5], v[6:7], v[24:25]
	s_nop 0
	v_pk_mul_f32 v[6:7], v[2:3], v[4:5] op_sel_hi:[0,1]
	v_pk_fma_f32 v[22:23], v[0:1], v[4:5], v[6:7] op_sel:[0,0,1] op_sel_hi:[1,1,0] neg_lo:[0,0,1] neg_hi:[0,0,1]
	v_pk_fma_f32 v[4:5], v[0:1], v[4:5], v[6:7] op_sel:[0,0,1] op_sel_hi:[0,1,0]
	v_mov_b32_e32 v23, v5
	s_waitcnt lgkmcnt(5)
	v_pk_add_f32 v[4:5], v[8:9], v[22:23]
	s_nop 0
	v_pk_mul_f32 v[6:7], v[2:3], v[4:5] op_sel_hi:[0,1]
	v_pk_fma_f32 v[8:9], v[0:1], v[4:5], v[6:7] op_sel:[0,0,1] op_sel_hi:[1,1,0] neg_lo:[0,0,1] neg_hi:[0,0,1]
	v_pk_fma_f32 v[4:5], v[0:1], v[4:5], v[6:7] op_sel:[0,0,1] op_sel_hi:[0,1,0]
	v_mov_b32_e32 v9, v5
	s_waitcnt lgkmcnt(4)
	v_pk_add_f32 v[4:5], v[12:13], v[8:9]
	s_nop 0
	v_pk_mul_f32 v[6:7], v[2:3], v[4:5] op_sel_hi:[0,1]
	v_pk_fma_f32 v[8:9], v[0:1], v[4:5], v[6:7] op_sel:[0,0,1] op_sel_hi:[1,1,0] neg_lo:[0,0,1] neg_hi:[0,0,1]
	v_pk_fma_f32 v[4:5], v[0:1], v[4:5], v[6:7] op_sel:[0,0,1] op_sel_hi:[0,1,0]
	v_mov_b32_e32 v9, v5
	s_waitcnt lgkmcnt(3)
	v_pk_add_f32 v[4:5], v[14:15], v[8:9]
	s_nop 0
	v_pk_mul_f32 v[6:7], v[2:3], v[4:5] op_sel_hi:[0,1]
	v_pk_fma_f32 v[8:9], v[0:1], v[4:5], v[6:7] op_sel:[0,0,1] op_sel_hi:[1,1,0] neg_lo:[0,0,1] neg_hi:[0,0,1]
	v_pk_fma_f32 v[4:5], v[0:1], v[4:5], v[6:7] op_sel:[0,0,1] op_sel_hi:[0,1,0]
	v_mov_b32_e32 v9, v5
	s_waitcnt lgkmcnt(2)
	v_pk_add_f32 v[4:5], v[16:17], v[8:9]
	s_nop 0
	v_pk_mul_f32 v[6:7], v[2:3], v[4:5] op_sel_hi:[0,1]
	v_pk_fma_f32 v[8:9], v[0:1], v[4:5], v[6:7] op_sel:[0,0,1] op_sel_hi:[1,1,0] neg_lo:[0,0,1] neg_hi:[0,0,1]
	v_pk_fma_f32 v[4:5], v[0:1], v[4:5], v[6:7] op_sel:[0,0,1] op_sel_hi:[0,1,0]
	v_mov_b32_e32 v9, v5
	s_waitcnt lgkmcnt(1)
	v_pk_add_f32 v[8:9], v[18:19], v[8:9]
	ds_read2st64_b32 v[4:5], v10 offset0:16 offset1:17
	ds_read2st64_b32 v[6:7], v10 offset0:18 offset1:19
	ds_read2st64_b32 v[12:13], v10 offset0:20 offset1:21
	ds_read2st64_b32 v[14:15], v10 offset0:22 offset1:23
	ds_read2st64_b32 v[16:17], v10 offset0:24 offset1:25
	ds_read2st64_b32 v[22:23], v10 offset0:26 offset1:27
	ds_read2st64_b32 v[24:25], v10 offset0:28 offset1:29
	ds_read2st64_b32 v[26:27], v10 offset0:30 offset1:31
	v_pk_mul_f32 v[18:19], v[2:3], v[8:9] op_sel_hi:[0,1]
	v_pk_fma_f32 v[28:29], v[0:1], v[8:9], v[18:19] op_sel:[0,0,1] op_sel_hi:[1,1,0] neg_lo:[0,0,1] neg_hi:[0,0,1]
	v_pk_fma_f32 v[8:9], v[0:1], v[8:9], v[18:19] op_sel:[0,0,1] op_sel_hi:[0,1,0]
	v_mov_b32_e32 v29, v9
	s_waitcnt lgkmcnt(8)
	v_pk_add_f32 v[8:9], v[20:21], v[28:29]
	s_nop 0
	v_pk_mul_f32 v[18:19], v[2:3], v[8:9] op_sel_hi:[0,1]
	v_pk_fma_f32 v[20:21], v[0:1], v[8:9], v[18:19] op_sel:[0,0,1] op_sel_hi:[1,1,0] neg_lo:[0,0,1] neg_hi:[0,0,1]
	v_pk_fma_f32 v[8:9], v[0:1], v[8:9], v[18:19] op_sel:[0,0,1] op_sel_hi:[0,1,0]
	v_mov_b32_e32 v21, v9
	s_waitcnt lgkmcnt(7)
	v_pk_add_f32 v[4:5], v[4:5], v[20:21]
	s_nop 0
	v_pk_mul_f32 v[8:9], v[2:3], v[4:5] op_sel_hi:[0,1]
	v_pk_fma_f32 v[18:19], v[0:1], v[4:5], v[8:9] op_sel:[0,0,1] op_sel_hi:[1,1,0] neg_lo:[0,0,1] neg_hi:[0,0,1]
	v_pk_fma_f32 v[4:5], v[0:1], v[4:5], v[8:9] op_sel:[0,0,1] op_sel_hi:[0,1,0]
	v_mov_b32_e32 v19, v5
	s_waitcnt lgkmcnt(6)
	v_pk_add_f32 v[4:5], v[6:7], v[18:19]
	v_mov_b32_e32 v1, v2
	v_mul_f32_e32 v6, v0, v4
	v_pk_fma_f32 v[6:7], v[0:1], v[4:5], v[6:7] op_sel_hi:[1,1,0] neg_lo:[1,0,0] neg_hi:[1,0,0]
	v_mov_b32_e32 v3, v0
	v_mul_f32_e32 v6, v0, v5
	v_pk_fma_f32 v[4:5], v[2:3], v[4:5], v[6:7] op_sel_hi:[1,1,0]
	s_waitcnt lgkmcnt(5)
	v_mov_b32_e32 v8, v13
	v_mov_b32_e32 v9, v12
	v_mov_b32_e32 v5, v7
	v_pk_add_f32 v[4:5], v[8:9], v[4:5]
	s_nop 0
	v_pk_mul_f32 v[6:7], v[2:3], v[4:5] op_sel_hi:[0,1]
	v_pk_fma_f32 v[8:9], v[0:1], v[4:5], v[6:7] op_sel:[0,0,1] op_sel_hi:[1,1,0]
	v_pk_fma_f32 v[4:5], v[0:1], v[4:5], v[6:7] op_sel:[0,0,1] op_sel_hi:[0,1,0] neg_lo:[0,0,1] neg_hi:[0,0,1]
	v_mov_b32_e32 v9, v5
	s_waitcnt lgkmcnt(4)
	v_mov_b32_e32 v4, v15
	v_mov_b32_e32 v5, v14
	v_pk_add_f32 v[4:5], v[4:5], v[8:9]
	s_nop 0
	v_pk_mul_f32 v[6:7], v[2:3], v[4:5] op_sel_hi:[0,1]
	v_pk_fma_f32 v[8:9], v[0:1], v[4:5], v[6:7] op_sel:[0,0,1] op_sel_hi:[1,1,0]
	v_pk_fma_f32 v[4:5], v[0:1], v[4:5], v[6:7] op_sel:[0,0,1] op_sel_hi:[0,1,0] neg_lo:[0,0,1] neg_hi:[0,0,1]
	v_mov_b32_e32 v9, v5
	s_waitcnt lgkmcnt(3)
	v_mov_b32_e32 v4, v17
	v_mov_b32_e32 v5, v16
	v_pk_add_f32 v[4:5], v[4:5], v[8:9]
	s_nop 0
	v_pk_mul_f32 v[6:7], v[2:3], v[4:5] op_sel_hi:[0,1]
	v_pk_fma_f32 v[8:9], v[0:1], v[4:5], v[6:7] op_sel:[0,0,1] op_sel_hi:[1,1,0]
	v_pk_fma_f32 v[4:5], v[0:1], v[4:5], v[6:7] op_sel:[0,0,1] op_sel_hi:[0,1,0] neg_lo:[0,0,1] neg_hi:[0,0,1]
	v_mov_b32_e32 v9, v5
	s_waitcnt lgkmcnt(2)
	v_mov_b32_e32 v4, v23
	v_mov_b32_e32 v5, v22
	v_pk_add_f32 v[4:5], v[4:5], v[8:9]
	ds_read2st64_b32 v[6:7], v10 offset0:32 offset1:33
	ds_read2st64_b32 v[8:9], v10 offset0:34 offset1:35
	ds_read2st64_b32 v[12:13], v10 offset0:36 offset1:37
	ds_read2st64_b32 v[14:15], v10 offset0:38 offset1:39
	ds_read2st64_b32 v[16:17], v10 offset0:40 offset1:41
	ds_read2st64_b32 v[18:19], v10 offset0:42 offset1:43
	ds_read2st64_b32 v[20:21], v10 offset0:44 offset1:45
	ds_read2st64_b32 v[22:23], v10 offset0:46 offset1:47
	v_pk_mul_f32 v[28:29], v[2:3], v[4:5] op_sel_hi:[0,1]
	v_pk_fma_f32 v[30:31], v[0:1], v[4:5], v[28:29] op_sel:[0,0,1] op_sel_hi:[1,1,0]
	v_pk_fma_f32 v[4:5], v[0:1], v[4:5], v[28:29] op_sel:[0,0,1] op_sel_hi:[0,1,0] neg_lo:[0,0,1] neg_hi:[0,0,1]
	v_mov_b32_e32 v31, v5
	s_waitcnt lgkmcnt(9)
	v_mov_b32_e32 v4, v25
	v_mov_b32_e32 v5, v24
	v_pk_add_f32 v[4:5], v[4:5], v[30:31]
	s_nop 0
	v_pk_mul_f32 v[24:25], v[2:3], v[4:5] op_sel_hi:[0,1]
	v_pk_fma_f32 v[28:29], v[0:1], v[4:5], v[24:25] op_sel:[0,0,1] op_sel_hi:[1,1,0]
	v_pk_fma_f32 v[4:5], v[0:1], v[4:5], v[24:25] op_sel:[0,0,1] op_sel_hi:[0,1,0] neg_lo:[0,0,1] neg_hi:[0,0,1]
	v_mov_b32_e32 v29, v5
	s_waitcnt lgkmcnt(8)
	v_mov_b32_e32 v4, v27
	v_mov_b32_e32 v5, v26
	v_pk_add_f32 v[4:5], v[4:5], v[28:29]
	s_nop 0
	v_pk_mul_f32 v[24:25], v[2:3], v[4:5] op_sel_hi:[0,1]
	v_pk_fma_f32 v[26:27], v[0:1], v[4:5], v[24:25] op_sel:[0,0,1] op_sel_hi:[1,1,0]
	v_pk_fma_f32 v[4:5], v[0:1], v[4:5], v[24:25] op_sel:[0,0,1] op_sel_hi:[0,1,0] neg_lo:[0,0,1] neg_hi:[0,0,1]
	v_mov_b32_e32 v27, v5
	s_waitcnt lgkmcnt(7)
	v_mov_b32_e32 v4, v7
	v_mov_b32_e32 v5, v6
	v_pk_add_f32 v[4:5], v[4:5], v[26:27]
	s_nop 0
	v_pk_mul_f32 v[6:7], v[2:3], v[4:5] op_sel_hi:[0,1]
	v_pk_fma_f32 v[24:25], v[0:1], v[4:5], v[6:7] op_sel:[0,0,1] op_sel_hi:[1,1,0]
	v_pk_fma_f32 v[4:5], v[0:1], v[4:5], v[6:7] op_sel:[0,0,1] op_sel_hi:[0,1,0] neg_lo:[0,0,1] neg_hi:[0,0,1]
	v_mov_b32_e32 v25, v5
	s_waitcnt lgkmcnt(6)
	v_mov_b32_e32 v4, v9
	v_mov_b32_e32 v5, v8
	v_pk_add_f32 v[4:5], v[4:5], v[24:25]
	s_nop 0
	v_pk_mul_f32 v[6:7], v[2:3], v[4:5] op_sel_hi:[0,1]
	v_pk_fma_f32 v[8:9], v[0:1], v[4:5], v[6:7] op_sel:[0,0,1] op_sel_hi:[1,1,0]
	v_pk_fma_f32 v[4:5], v[0:1], v[4:5], v[6:7] op_sel:[0,0,1] op_sel_hi:[0,1,0] neg_lo:[0,0,1] neg_hi:[0,0,1]
	v_mov_b32_e32 v9, v5
	s_waitcnt lgkmcnt(5)
	v_mov_b32_e32 v4, v13
	v_mov_b32_e32 v5, v12
	v_pk_add_f32 v[4:5], v[4:5], v[8:9]
	s_nop 0
	v_pk_mul_f32 v[6:7], v[2:3], v[4:5] op_sel_hi:[0,1]
	v_pk_fma_f32 v[8:9], v[0:1], v[4:5], v[6:7] op_sel:[0,0,1] op_sel_hi:[1,1,0]
	v_pk_fma_f32 v[4:5], v[0:1], v[4:5], v[6:7] op_sel:[0,0,1] op_sel_hi:[0,1,0] neg_lo:[0,0,1] neg_hi:[0,0,1]
	v_mov_b32_e32 v9, v5
	s_waitcnt lgkmcnt(4)
	v_mov_b32_e32 v4, v15
	v_mov_b32_e32 v5, v14
	v_pk_add_f32 v[4:5], v[4:5], v[8:9]
	s_nop 0
	v_pk_mul_f32 v[6:7], v[2:3], v[4:5] op_sel_hi:[0,1]
	v_pk_fma_f32 v[8:9], v[0:1], v[4:5], v[6:7] op_sel:[0,0,1] op_sel_hi:[1,1,0]
	v_pk_fma_f32 v[4:5], v[0:1], v[4:5], v[6:7] op_sel:[0,0,1] op_sel_hi:[0,1,0] neg_lo:[0,0,1] neg_hi:[0,0,1]
	v_mov_b32_e32 v9, v5
	s_waitcnt lgkmcnt(3)
	v_mov_b32_e32 v4, v17
	v_mov_b32_e32 v5, v16
	v_pk_add_f32 v[4:5], v[4:5], v[8:9]
	s_nop 0
	v_mul_f32_e32 v6, v0, v5
	v_mul_f32_e32 v8, v0, v4
	v_pk_fma_f32 v[6:7], v[2:3], v[4:5], v[6:7] op_sel_hi:[1,1,0] neg_lo:[1,0,0] neg_hi:[1,0,0]
	v_pk_fma_f32 v[4:5], v[0:1], v[4:5], v[8:9] op_sel_hi:[1,1,0]
	ds_read2st64_b32 v[8:9], v10 offset0:48 offset1:49
	ds_read2st64_b32 v[12:13], v10 offset0:50 offset1:51
	ds_read2st64_b32 v[14:15], v10 offset0:52 offset1:53
	ds_read2st64_b32 v[16:17], v10 offset0:54 offset1:55
	ds_read2st64_b32 v[24:25], v10 offset0:56 offset1:57
	ds_read2st64_b32 v[26:27], v10 offset0:58 offset1:59
	ds_read2st64_b32 v[28:29], v10 offset0:60 offset1:61
	ds_read2st64_b32 v[30:31], v10 offset0:62 offset1:63
	v_mov_b32_e32 v7, v5
	s_waitcnt lgkmcnt(10)
	v_pk_add_f32 v[4:5], v[18:19], v[6:7]
	s_nop 0
	v_pk_mul_f32 v[6:7], v[2:3], v[4:5] op_sel_hi:[0,1]
	v_pk_fma_f32 v[18:19], v[0:1], v[4:5], v[6:7] op_sel:[0,0,1] op_sel_hi:[1,1,0] neg_lo:[0,0,1] neg_hi:[0,0,1]
	v_pk_fma_f32 v[4:5], v[0:1], v[4:5], v[6:7] op_sel:[0,0,1] op_sel_hi:[0,1,0]
	v_mov_b32_e32 v19, v5
	s_waitcnt lgkmcnt(9)
	v_pk_add_f32 v[4:5], v[20:21], v[18:19]
	s_nop 0
	v_pk_mul_f32 v[6:7], v[2:3], v[4:5] op_sel_hi:[0,1]
	v_pk_fma_f32 v[18:19], v[0:1], v[4:5], v[6:7] op_sel:[0,0,1] op_sel_hi:[1,1,0] neg_lo:[0,0,1] neg_hi:[0,0,1]
	v_pk_fma_f32 v[4:5], v[0:1], v[4:5], v[6:7] op_sel:[0,0,1] op_sel_hi:[0,1,0]
	v_mov_b32_e32 v19, v5
	s_waitcnt lgkmcnt(8)
	v_pk_add_f32 v[4:5], v[22:23], v[18:19]
	s_nop 0
	v_pk_mul_f32 v[6:7], v[2:3], v[4:5] op_sel_hi:[0,1]
	v_pk_fma_f32 v[18:19], v[0:1], v[4:5], v[6:7] op_sel:[0,0,1] op_sel_hi:[1,1,0] neg_lo:[0,0,1] neg_hi:[0,0,1]
	v_pk_fma_f32 v[4:5], v[0:1], v[4:5], v[6:7] op_sel:[0,0,1] op_sel_hi:[0,1,0]
	v_mov_b32_e32 v19, v5
	s_waitcnt lgkmcnt(7)
	v_pk_add_f32 v[4:5], v[8:9], v[18:19]
	s_nop 0
	v_pk_mul_f32 v[6:7], v[2:3], v[4:5] op_sel_hi:[0,1]
	v_pk_fma_f32 v[8:9], v[0:1], v[4:5], v[6:7] op_sel:[0,0,1] op_sel_hi:[1,1,0] neg_lo:[0,0,1] neg_hi:[0,0,1]
	v_pk_fma_f32 v[4:5], v[0:1], v[4:5], v[6:7] op_sel:[0,0,1] op_sel_hi:[0,1,0]
	v_mov_b32_e32 v9, v5
	s_waitcnt lgkmcnt(6)
	v_pk_add_f32 v[4:5], v[12:13], v[8:9]
	s_nop 0
	v_pk_mul_f32 v[6:7], v[2:3], v[4:5] op_sel_hi:[0,1]
	v_pk_fma_f32 v[8:9], v[0:1], v[4:5], v[6:7] op_sel:[0,0,1] op_sel_hi:[1,1,0] neg_lo:[0,0,1] neg_hi:[0,0,1]
	v_pk_fma_f32 v[4:5], v[0:1], v[4:5], v[6:7] op_sel:[0,0,1] op_sel_hi:[0,1,0]
	v_mov_b32_e32 v9, v5
	s_waitcnt lgkmcnt(5)
	v_pk_add_f32 v[4:5], v[14:15], v[8:9]
	s_nop 0
	v_pk_mul_f32 v[6:7], v[2:3], v[4:5] op_sel_hi:[0,1]
	v_pk_fma_f32 v[8:9], v[0:1], v[4:5], v[6:7] op_sel:[0,0,1] op_sel_hi:[1,1,0] neg_lo:[0,0,1] neg_hi:[0,0,1]
	v_pk_fma_f32 v[4:5], v[0:1], v[4:5], v[6:7] op_sel:[0,0,1] op_sel_hi:[0,1,0]
	v_mov_b32_e32 v9, v5
	s_waitcnt lgkmcnt(4)
	v_pk_add_f32 v[4:5], v[16:17], v[8:9]
	s_nop 0
	v_pk_mul_f32 v[6:7], v[2:3], v[4:5] op_sel_hi:[0,1]
	v_pk_fma_f32 v[8:9], v[0:1], v[4:5], v[6:7] op_sel:[0,0,1] op_sel_hi:[1,1,0] neg_lo:[0,0,1] neg_hi:[0,0,1]
	v_pk_fma_f32 v[4:5], v[0:1], v[4:5], v[6:7] op_sel:[0,0,1] op_sel_hi:[0,1,0]
	v_mov_b32_e32 v9, v5
	v_lshl_add_u32 v1, v76, 3, 0
	s_waitcnt lgkmcnt(3)
	v_pk_add_f32 v[4:5], v[24:25], v[8:9]
	v_add_u32_e32 v1, 0x20000, v1
	v_pk_mul_f32 v[6:7], v[2:3], v[4:5] op_sel_hi:[0,1]
	v_pk_fma_f32 v[8:9], v[0:1], v[4:5], v[6:7] op_sel:[0,0,1] op_sel_hi:[1,1,0] neg_lo:[0,0,1] neg_hi:[0,0,1]
	v_pk_fma_f32 v[4:5], v[0:1], v[4:5], v[6:7] op_sel:[0,0,1] op_sel_hi:[0,1,0]
	v_mov_b32_e32 v9, v5
	s_waitcnt lgkmcnt(2)
	v_pk_add_f32 v[4:5], v[26:27], v[8:9]
	s_nop 0
	v_pk_mul_f32 v[6:7], v[2:3], v[4:5] op_sel_hi:[0,1]
	v_pk_fma_f32 v[8:9], v[0:1], v[4:5], v[6:7] op_sel:[0,0,1] op_sel_hi:[1,1,0] neg_lo:[0,0,1] neg_hi:[0,0,1]
	v_pk_fma_f32 v[4:5], v[0:1], v[4:5], v[6:7] op_sel:[0,0,1] op_sel_hi:[0,1,0]
	v_mov_b32_e32 v9, v5
	s_waitcnt lgkmcnt(1)
	v_pk_add_f32 v[4:5], v[28:29], v[8:9]
	s_nop 0
	v_pk_mul_f32 v[6:7], v[2:3], v[4:5] op_sel_hi:[0,1]
	v_pk_fma_f32 v[8:9], v[0:1], v[4:5], v[6:7] op_sel:[0,0,1] op_sel_hi:[1,1,0] neg_lo:[0,0,1] neg_hi:[0,0,1]
	v_pk_fma_f32 v[4:5], v[0:1], v[4:5], v[6:7] op_sel:[0,0,1] op_sel_hi:[0,1,0]
	v_mov_b32_e32 v9, v5
	s_waitcnt lgkmcnt(0)
	v_pk_add_f32 v[4:5], v[30:31], v[8:9]
	ds_write_b64 v1, v[4:5]
	v_mov_b32_e32 v5, 0
	v_mov_b32_e32 v4, 0
	s_waitcnt lgkmcnt(0)
	s_barrier
	s_cbranch_vccnz .LBB5_381
	v_mul_f32_e32 v3, v2, v2
	v_add_f32_e32 v1, v0, v0
	v_fma_f32 v3, v0, v0, -v3
	v_mul_f32_e32 v1, v1, v2
	v_add_f32_e32 v4, v3, v3
	v_mul_f32_e32 v4, v1, v4
	v_mul_f32_e32 v1, v1, v1
	v_fma_f32 v1, v3, v3, -v1
	v_add_f32_e32 v3, v1, v1
	v_mul_f32_e32 v3, v4, v3
	v_mul_f32_e32 v4, v4, v4
	v_fma_f32 v1, v1, v1, -v4
	v_add_f32_e32 v4, v1, v1
	v_mul_f32_e32 v4, v3, v4
	v_mul_f32_e32 v3, v3, v3
	v_fma_f32 v1, v1, v1, -v3
	v_add_f32_e32 v3, v1, v1
	v_mul_f32_e32 v6, v4, v3
	v_mul_f32_e32 v3, v4, v4
	v_fma_f32 v8, v1, v1, -v3
	v_lshlrev_b32_e32 v1, 3, v84
	s_andn2_b64 vcc, exec, s[12:13]
	v_mov_b32_e32 v9, v8
	s_cbranch_vccnz .LBB5_378
	s_add_i32 s0, 0, 0x20000
	v_mov_b32_e32 v4, 0
	v_mov_b32_e32 v7, v6
	v_add_u32_e32 v3, s0, v1
	s_mov_b32 s0, 0
	v_mov_b32_e32 v5, v4
